# all eight phase seams on the shorter barrier protocol
# speedup vs baseline: 1.0202x; 1.0025x over previous
; __device__ __forceinline__ unsigned xb_ld(unsigned* p)              { return __hip_atomic_load(p, __ATOMIC_RELAXED, __HIP_MEMORY_SCOPE_AGENT); }
; __device__ __forceinline__ unsigned xb_add(unsigned* p, unsigned v) { return __hip_atomic_fetch_add(p, v, __ATOMIC_RELAXED, __HIP_MEMORY_SCOPE_AGENT); }
; #define XB_SPIN(cond, bar) do { unsigned _sp = 0; while (cond) { __builtin_amdgcn_s_sleep(1); \
;     if ((++_sp & 255u) == 0u) { if (xb_ld(&(bar)[XB_TMO])) break; if (_sp > XB_SPIN_CAP) { atomicAdd(&(bar)[XB_TMO], 1u); break; } } } } while (0)
; __device__ __forceinline__ void xcd_barrier(const XcdBarrier& b) {
;     asm volatile("s_waitcnt vmcnt(0)" ::: "memory");
;     __syncthreads();
;     if (threadIdx.x == 0) {
;         unsigned* bar = b.bar;
;         __builtin_amdgcn_s_waitcnt(0);
;         unsigned nloc = b.st[0], nx = b.st[1];
;         if (nloc == 0u) { xcd_barrier_complete(bar, b.x, nloc, nx); b.st[0] = nloc; b.st[1] = nx; }
;         const unsigned old = xb_add(&bar[XB_XSUB(b.x)], 1u);
;         const unsigned gen = old / nloc;
;         if (old + 1u == (gen + 1u) * nloc) {
;             __builtin_amdgcn_fence(__ATOMIC_RELEASE, "agent");
;             asm volatile("s_waitcnt vmcnt(0)" ::: "memory");
;             const unsigned og = xb_add(&bar[XB_TOP], 1u);
;             const unsigned tg = og / nx;
;             if (og + 1u == (tg + 1u) * nx) xb_add(&bar[XB_TOPGEN], 1u);
;             else XB_SPIN(xb_ld(&bar[XB_TOPGEN]) == tg, bar);
;             __builtin_amdgcn_fence(__ATOMIC_ACQUIRE, "agent");
;             xb_add(&bar[XB_XGEN(b.x)], 1u);
;             asm volatile("s_waitcnt vmcnt(0)" ::: "memory");
;         } else {
;             XB_SPIN(xb_ld(&bar[XB_XGEN(b.x)]) == gen, bar);
;             __builtin_amdgcn_fence(__ATOMIC_ACQUIRE, "agent");
;             asm volatile("s_waitcnt vmcnt(0)" ::: "memory");
;         }
;     }
;     __syncthreads();
; }
.LBB0_699:
	s_or_b32 s10, s58, 3
	s_cmp_ge_i32 s10, s19
	s_cbranch_scc1 .LBB0_711
	v_mov_b32_e32 v0, s42
	ds_read_b64 v[2:3], v0
	s_getreg_b32 s6, hwreg(HW_REG_XCC_ID, 0, 4)
	s_waitcnt vmcnt(0)
	s_waitcnt vmcnt(0) lgkmcnt(0)
	s_barrier
	v_readfirstlane_b32 s5, v3
	v_readfirstlane_b32 s4, v2
	s_and_saveexec_b64 s[0:1], s[78:79]
	s_movk_i32 s37, 0xb00
	s_movk_i32 s43, 0x51
	s_mul_i32 s48, s34, 3
	s_mul_hi_i32 s49, s34, 3
	v_readlane_b32 s50, v255, 33
	s_cbranch_execz .LBB0_753
	v_mov_b32_e32 v0, 0x250d0
	ds_read_b64 v[6:7], v0
	v_mov_b32_e32 v0, 0x25100
	ds_read2_b32 v[8:9], v0 offset1:2
	s_getreg_b32 s12, hwreg(HW_REG_XCC_ID, 0, 4)
	s_waitcnt vmcnt(0) lgkmcnt(0)
	v_readfirstlane_b32 s40, v6
	v_readfirstlane_b32 s41, v7
	v_readfirstlane_b32 s14, v8
	v_readfirstlane_b32 s17, v9
	s_add_u32 s40, s40, 0x1e600000
	s_addc_u32 s41, s41, 0
	s_and_b32 s12, s12, 15
	s_add_i32 s17, s17, 1
	v_mov_b32_e32 v8, s17
	ds_write_b32 v0, v8 offset:8
	s_mul_i32 s28, s17, s14
	s_mul_i32 s30, s17, s34
	s_lshl_b32 s31, s12, 8
	s_add_i32 s31, s31, 0x8000
	v_mov_b32_e32 v0, s31
	v_mov_b32_e32 v6, 1
	global_atomic_add v6, v0, v6, s[40:41] sc0
	s_waitcnt vmcnt(0)
	v_readfirstlane_b32 s31, v6
	s_add_i32 s31, s31, 1
	s_cmp_lg_u32 s31, s28
	s_cbranch_scc1 .LsbM_wait
	buffer_wbl2 sc1
	s_waitcnt vmcnt(0)
	v_mov_b32_e32 v0, 0x9000
	v_mov_b32_e32 v6, s14
	global_atomic_add v0, v6, s[40:41]

; __device__ __forceinline__ unsigned xb_ld(unsigned* p)              { return __hip_atomic_load(p, __ATOMIC_RELAXED, __HIP_MEMORY_SCOPE_AGENT); }
; __device__ __forceinline__ unsigned xb_add(unsigned* p, unsigned v) { return __hip_atomic_fetch_add(p, v, __ATOMIC_RELAXED, __HIP_MEMORY_SCOPE_AGENT); }
; #define XB_SPIN(cond, bar) do { unsigned _sp = 0; while (cond) { __builtin_amdgcn_s_sleep(1); \
;     if ((++_sp & 255u) == 0u) { if (xb_ld(&(bar)[XB_TMO])) break; if (_sp > XB_SPIN_CAP) { atomicAdd(&(bar)[XB_TMO], 1u); break; } } } } while (0)
; __device__ __forceinline__ void xcd_barrier(const XcdBarrier& b) {
;     ...
;         const unsigned old = xb_add(&bar[XB_XSUB(b.x)], 1u);
;         const unsigned gen = old / nloc;
;         if (old + 1u == (gen + 1u) * nloc) {
;             __builtin_amdgcn_fence(__ATOMIC_RELEASE, "agent");
;             asm volatile("s_waitcnt vmcnt(0)" ::: "memory");
;             const unsigned og = xb_add(&bar[XB_TOP], 1u);
;             const unsigned tg = og / nx;
;             if (og + 1u == (tg + 1u) * nx) xb_add(&bar[XB_TOPGEN], 1u);
;             else XB_SPIN(xb_ld(&bar[XB_TOPGEN]) == tg, bar);
;             __builtin_amdgcn_fence(__ATOMIC_ACQUIRE, "agent");
;             xb_add(&bar[XB_XGEN(b.x)], 1u);
;             asm volatile("s_waitcnt vmcnt(0)" ::: "memory");
;         } else {
;             XB_SPIN(xb_ld(&bar[XB_XGEN(b.x)]) == gen, bar);
;             __builtin_amdgcn_fence(__ATOMIC_ACQUIRE, "agent");
;             asm volatile("s_waitcnt vmcnt(0)" ::: "memory");
;         }
;     }
;     __syncthreads();
; }
.LsbM_acq:
	buffer_inv sc1
	s_waitcnt vmcnt(0) lgkmcnt(0)
	s_branch .LBB0_753
.LBB0_711:
	s_movk_i32 s37, 0xb00
	s_movk_i32 s43, 0x51
	s_mul_i32 s48, s34, 3
	s_mul_hi_i32 s49, s34, 3
	v_readlane_b32 s50, v255, 33
	s_branch .LBB0_754
.LBB0_753:
	s_or_b64 exec, exec, s[0:1]
	s_waitcnt lgkmcnt(0)
	s_barrier

; __device__ __forceinline__ unsigned xb_ld(unsigned* p)              { return __hip_atomic_load(p, __ATOMIC_RELAXED, __HIP_MEMORY_SCOPE_AGENT); }
; __device__ __forceinline__ unsigned xb_add(unsigned* p, unsigned v) { return __hip_atomic_fetch_add(p, v, __ATOMIC_RELAXED, __HIP_MEMORY_SCOPE_AGENT); }
; #define XB_SPIN(cond, bar) do { unsigned _sp = 0; while (cond) { __builtin_amdgcn_s_sleep(1); \
;     if ((++_sp & 255u) == 0u) { if (xb_ld(&(bar)[XB_TMO])) break; if (_sp > XB_SPIN_CAP) { atomicAdd(&(bar)[XB_TMO], 1u); break; } } } } while (0)
; __device__ __forceinline__ void xcd_barrier(const XcdBarrier& b) {
;     asm volatile("s_waitcnt vmcnt(0)" ::: "memory");
;     __syncthreads();
;     if (threadIdx.x == 0) {
;         unsigned* bar = b.bar;
;         __builtin_amdgcn_s_waitcnt(0);
;         unsigned nloc = b.st[0], nx = b.st[1];
;         if (nloc == 0u) { xcd_barrier_complete(bar, b.x, nloc, nx); b.st[0] = nloc; b.st[1] = nx; }
;         const unsigned old = xb_add(&bar[XB_XSUB(b.x)], 1u);
;         const unsigned gen = old / nloc;
;         if (old + 1u == (gen + 1u) * nloc) {
;             __builtin_amdgcn_fence(__ATOMIC_RELEASE, "agent");
;             asm volatile("s_waitcnt vmcnt(0)" ::: "memory");
;             const unsigned og = xb_add(&bar[XB_TOP], 1u);
;             const unsigned tg = og / nx;
;             if (og + 1u == (tg + 1u) * nx) xb_add(&bar[XB_TOPGEN], 1u);
;             else XB_SPIN(xb_ld(&bar[XB_TOPGEN]) == tg, bar);
;             __builtin_amdgcn_fence(__ATOMIC_ACQUIRE, "agent");
;             xb_add(&bar[XB_XGEN(b.x)], 1u);
;             asm volatile("s_waitcnt vmcnt(0)" ::: "memory");
;         } else {
;             XB_SPIN(xb_ld(&bar[XB_XGEN(b.x)]) == gen, bar);
;             __builtin_amdgcn_fence(__ATOMIC_ACQUIRE, "agent");
;             asm volatile("s_waitcnt vmcnt(0)" ::: "memory");
;         }
;     }
;     __syncthreads();
; }
.LBB0_1366:
	v_mov_b32_e32 v0, 0x250d0
	ds_read_b64 v[6:7], v0
	v_mov_b32_e32 v0, 0x25100
	ds_read2_b32 v[8:9], v0 offset1:2
	s_getreg_b32 s12, hwreg(HW_REG_XCC_ID, 0, 4)
	s_waitcnt vmcnt(0) lgkmcnt(0)
	v_readfirstlane_b32 s40, v6
	v_readfirstlane_b32 s41, v7
	v_readfirstlane_b32 s14, v8
	v_readfirstlane_b32 s17, v9
	s_add_u32 s40, s40, 0x1e600000
	s_addc_u32 s41, s41, 0
	s_and_b32 s12, s12, 15
	s_add_i32 s17, s17, 1
	v_mov_b32_e32 v8, s17
	ds_write_b32 v0, v8 offset:8
	s_mul_i32 s28, s17, s14
	s_mul_i32 s30, s17, s34
	s_lshl_b32 s31, s12, 8
	s_add_i32 s31, s31, 0x8000
	v_mov_b32_e32 v0, s31
	v_mov_b32_e32 v6, 1
	global_atomic_add v6, v0, v6, s[40:41] sc0
	s_waitcnt vmcnt(0)
	v_readfirstlane_b32 s31, v6
	s_add_i32 s31, s31, 1
	s_cmp_lg_u32 s31, s28
	s_cbranch_scc1 .LsbL_wait
	buffer_wbl2 sc1
	s_waitcnt vmcnt(0)
	v_mov_b32_e32 v0, 0x9000
	v_mov_b32_e32 v6, s14
	global_atomic_add v0, v6, s[40:41]

; __device__ __forceinline__ unsigned xb_ld(unsigned* p)              { return __hip_atomic_load(p, __ATOMIC_RELAXED, __HIP_MEMORY_SCOPE_AGENT); }
; __device__ __forceinline__ unsigned xb_add(unsigned* p, unsigned v) { return __hip_atomic_fetch_add(p, v, __ATOMIC_RELAXED, __HIP_MEMORY_SCOPE_AGENT); }
; #define XB_SPIN(cond, bar) do { unsigned _sp = 0; while (cond) { __builtin_amdgcn_s_sleep(1); \
;     if ((++_sp & 255u) == 0u) { if (xb_ld(&(bar)[XB_TMO])) break; if (_sp > XB_SPIN_CAP) { atomicAdd(&(bar)[XB_TMO], 1u); break; } } } } while (0)
; __device__ __forceinline__ void xcd_barrier(const XcdBarrier& b) {
;     ...
;         const unsigned old = xb_add(&bar[XB_XSUB(b.x)], 1u);
;         const unsigned gen = old / nloc;
;         if (old + 1u == (gen + 1u) * nloc) {
;             __builtin_amdgcn_fence(__ATOMIC_RELEASE, "agent");
;             asm volatile("s_waitcnt vmcnt(0)" ::: "memory");
;             const unsigned og = xb_add(&bar[XB_TOP], 1u);
;             const unsigned tg = og / nx;
;             if (og + 1u == (tg + 1u) * nx) xb_add(&bar[XB_TOPGEN], 1u);
;             else XB_SPIN(xb_ld(&bar[XB_TOPGEN]) == tg, bar);
;             __builtin_amdgcn_fence(__ATOMIC_ACQUIRE, "agent");
;             xb_add(&bar[XB_XGEN(b.x)], 1u);
;             asm volatile("s_waitcnt vmcnt(0)" ::: "memory");
;         } else {
;             XB_SPIN(xb_ld(&bar[XB_XGEN(b.x)]) == gen, bar);
;             __builtin_amdgcn_fence(__ATOMIC_ACQUIRE, "agent");
;             asm volatile("s_waitcnt vmcnt(0)" ::: "memory");
;         }
;     }
;     __syncthreads();
; }
.LsbL_acq:
	buffer_inv sc1
	s_waitcnt vmcnt(0) lgkmcnt(0)
	s_getpc_b64 s[98:99]
